# p3 h2 items: chunk loop unrolled and software pipelined (next step's loads before the dependent chain)
# baseline (speedup 1.0000x reference)
; DEVI float b2f(bfu b) { return __uint_as_float(((unsigned)b) << 16); }
; DEVI void h2_item(const Params& P, int l, int pass, int item, int tid) {
;     ...
;   for (int c0 = 0; c0 < 64; c0 += 8) {
;     float u[8], dc[8];
; #pragma unroll
;     for (int i = 0; i < 8; ++i) { u[i] = b2f(US[(long)(c0 + i) << 14]); dc[i] = dec[(c0 + i) * 128]; }
; #pragma unroll
;     for (int i = 0; i < 8; ++i) { US[(long)(c0 + i) << 14] = f2b(S); S = dc[i] * S + u[i]; }
;   }
.LBB0_455:
	v_lshl_add_u64 v[6:7], v[64:65], 0, v[0:1]
	v_add_co_u32_e32 v10, vcc, 0x8000, v6
	s_mov_b32 s46, 0x10000
	s_nop 0
	v_addc_co_u32_e32 v11, vcc, 0, v7, vcc
	v_add_co_u32_e32 v12, vcc, s46, v6
	v_lshl_add_u64 v[8:9], v[64:65], 0, v[2:3]
	s_nop 0
	v_addc_co_u32_e32 v13, vcc, 0, v7, vcc
	v_add_co_u32_e32 v14, vcc, 0x18000, v6
	global_load_ushort v5, v[6:7], off
	global_load_dword v41, v[8:9], off
	global_load_dword v43, v[8:9], off offset:512
	global_load_dword v45, v[8:9], off offset:1024
	global_load_dword v47, v[8:9], off offset:1536
	global_load_dword v52, v[8:9], off offset:2048
	global_load_dword v53, v[8:9], off offset:2560
	global_load_dword v54, v[8:9], off offset:3072
	v_addc_co_u32_e32 v15, vcc, 0, v7, vcc
	v_add_co_u32_e32 v16, vcc, s6, v6
	global_load_ushort v55, v[10:11], off
	global_load_ushort v56, v[12:13], off
	v_addc_co_u32_e32 v17, vcc, 0, v7, vcc
	v_add_co_u32_e32 v18, vcc, 0x28000, v6
	global_load_ushort v57, v[14:15], off
	global_load_ushort v58, v[16:17], off
	v_addc_co_u32_e32 v19, vcc, 0, v7, vcc
	v_add_co_u32_e32 v48, vcc, 0x30000, v6
	global_load_ushort v59, v[18:19], off
	s_nop 0
	v_addc_co_u32_e32 v49, vcc, 0, v7, vcc
	v_add_co_u32_e32 v50, vcc, 0x38000, v6
	global_load_ushort v60, v[48:49], off
	s_nop 0
	v_addc_co_u32_e32 v51, vcc, 0, v7, vcc
	global_load_ushort v61, v[50:51], off
	s_nop 0
	global_load_dword v8, v[8:9], off offset:3584
	v_lshl_add_u64 v[0:1], v[0:1], 0, s[8:9]
	v_lshl_add_u64 v[2:3], v[2:3], 0, s[4:5]
	v_lshl_add_u64 v[212:213], v[64:65], 0, v[0:1]
	v_add_co_u32_e32 v216, vcc, 0x8000, v212
	s_mov_b32 s46, 0x10000
	s_nop 0
	v_addc_co_u32_e32 v217, vcc, 0, v213, vcc
	v_add_co_u32_e32 v218, vcc, s46, v212
	v_lshl_add_u64 v[214:215], v[64:65], 0, v[2:3]
	s_nop 0
	v_addc_co_u32_e32 v219, vcc, 0, v213, vcc
	v_add_co_u32_e32 v220, vcc, 0x18000, v212
	global_load_ushort v196, v[212:213], off
	global_load_dword v197, v[214:215], off
	global_load_dword v198, v[214:215], off offset:512
	global_load_dword v199, v[214:215], off offset:1024
	global_load_dword v200, v[214:215], off offset:1536
	global_load_dword v201, v[214:215], off offset:2048
	global_load_dword v202, v[214:215], off offset:2560
	global_load_dword v203, v[214:215], off offset:3072
	v_addc_co_u32_e32 v221, vcc, 0, v213, vcc
	v_add_co_u32_e32 v222, vcc, s6, v212
	global_load_ushort v204, v[216:217], off
	global_load_ushort v205, v[218:219], off
	v_addc_co_u32_e32 v223, vcc, 0, v213, vcc
	v_add_co_u32_e32 v224, vcc, 0x28000, v212
	global_load_ushort v206, v[220:221], off
	global_load_ushort v207, v[222:223], off
	v_addc_co_u32_e32 v225, vcc, 0, v213, vcc
	v_add_co_u32_e32 v226, vcc, 0x30000, v212
	global_load_ushort v208, v[224:225], off
	s_nop 0
	v_addc_co_u32_e32 v227, vcc, 0, v213, vcc
	v_add_co_u32_e32 v228, vcc, 0x38000, v212
	global_load_ushort v209, v[226:227], off
	s_nop 0
	v_addc_co_u32_e32 v229, vcc, 0, v213, vcc
	global_load_ushort v210, v[228:229], off
	s_nop 0
	global_load_dword v214, v[214:215], off offset:3584
	v_lshl_add_u64 v[0:1], v[0:1], 0, s[8:9]
	v_lshl_add_u64 v[2:3], v[2:3], 0, s[4:5]
	v_bfe_u32 v9, v4, 16, 1
	v_add3_u32 v9, v4, v9, s39
	global_store_short_d16_hi v[6:7], v9, off
	s_waitcnt vmcnt(32)
	v_lshlrev_b32_e32 v5, 16, v5
	s_waitcnt vmcnt(31)
	v_fmac_f32_e32 v5, v4, v41
	v_bfe_u32 v6, v5, 16, 1
	v_add3_u32 v6, v5, v6, s39
	global_store_short_d16_hi v[10:11], v6, off
	s_waitcnt vmcnt(25)
	v_lshlrev_b32_e32 v4, 16, v55
	s_waitcnt vmcnt(24)
	v_lshlrev_b32_e32 v7, 16, v56
	v_fmac_f32_e32 v4, v43, v5
	v_bfe_u32 v6, v4, 16, 1
	v_fmac_f32_e32 v7, v45, v4
	s_waitcnt vmcnt(23)
	v_lshlrev_b32_e32 v5, 16, v57
	s_waitcnt vmcnt(22)
	v_lshlrev_b32_e32 v9, 16, v58
	v_add3_u32 v4, v4, v6, s39
	v_bfe_u32 v6, v7, 16, 1
	v_fmac_f32_e32 v5, v47, v7
	global_store_short_d16_hi v[12:13], v4, off
	s_waitcnt vmcnt(22)
	v_lshlrev_b32_e32 v10, 16, v59
	v_add3_u32 v4, v7, v6, s39
	v_bfe_u32 v6, v5, 16, 1
	v_fmac_f32_e32 v9, v52, v5
	global_store_short_d16_hi v[14:15], v4, off
	s_waitcnt vmcnt(22)
	v_lshlrev_b32_e32 v7, 16, v60
	v_add3_u32 v4, v5, v6, s39
	v_bfe_u32 v5, v9, 16, 1
	v_fmac_f32_e32 v10, v53, v9
	s_waitcnt vmcnt(21)
	v_lshlrev_b32_e32 v6, 16, v61
	global_store_short_d16_hi v[16:17], v4, off
	v_add3_u32 v4, v9, v5, s39
	v_bfe_u32 v5, v10, 16, 1
	v_fmac_f32_e32 v7, v54, v10
	global_store_short_d16_hi v[18:19], v4, off
	v_add3_u32 v5, v10, v5, s39
	v_bfe_u32 v9, v7, 16, 1
	v_mov_b32_e32 v4, v6
	global_store_short_d16_hi v[48:49], v5, off
	v_add3_u32 v5, v7, v9, s39
	s_waitcnt vmcnt(23)
	v_fmac_f32_e32 v4, v8, v7
	global_store_short_d16_hi v[50:51], v5, off
	v_lshl_add_u64 v[6:7], v[64:65], 0, v[0:1]
	v_add_co_u32_e32 v10, vcc, 0x8000, v6
	s_mov_b32 s46, 0x10000
	s_nop 0
	v_addc_co_u32_e32 v11, vcc, 0, v7, vcc
	v_add_co_u32_e32 v12, vcc, s46, v6
	v_lshl_add_u64 v[8:9], v[64:65], 0, v[2:3]
	s_nop 0
	v_addc_co_u32_e32 v13, vcc, 0, v7, vcc
	v_add_co_u32_e32 v14, vcc, 0x18000, v6
	global_load_ushort v5, v[6:7], off
	global_load_dword v41, v[8:9], off
	global_load_dword v43, v[8:9], off offset:512
	global_load_dword v45, v[8:9], off offset:1024
	global_load_dword v47, v[8:9], off offset:1536
	global_load_dword v52, v[8:9], off offset:2048
	global_load_dword v53, v[8:9], off offset:2560
	global_load_dword v54, v[8:9], off offset:3072
	v_addc_co_u32_e32 v15, vcc, 0, v7, vcc
	v_add_co_u32_e32 v16, vcc, s6, v6
	global_load_ushort v55, v[10:11], off
	global_load_ushort v56, v[12:13], off
	v_addc_co_u32_e32 v17, vcc, 0, v7, vcc
	v_add_co_u32_e32 v18, vcc, 0x28000, v6
	global_load_ushort v57, v[14:15], off
	global_load_ushort v58, v[16:17], off
	v_addc_co_u32_e32 v19, vcc, 0, v7, vcc
	v_add_co_u32_e32 v48, vcc, 0x30000, v6
	global_load_ushort v59, v[18:19], off
	s_nop 0
	v_addc_co_u32_e32 v49, vcc, 0, v7, vcc
	v_add_co_u32_e32 v50, vcc, 0x38000, v6
	global_load_ushort v60, v[48:49], off
	s_nop 0
	v_addc_co_u32_e32 v51, vcc, 0, v7, vcc
	global_load_ushort v61, v[50:51], off
	s_nop 0
	global_load_dword v8, v[8:9], off offset:3584
	v_lshl_add_u64 v[0:1], v[0:1], 0, s[8:9]
	v_lshl_add_u64 v[2:3], v[2:3], 0, s[4:5]
	v_bfe_u32 v215, v4, 16, 1
	v_add3_u32 v215, v4, v215, s39
	global_store_short_d16_hi v[212:213], v215, off
	s_waitcnt vmcnt(40)
; DEVI float b2f(bfu b) { return __uint_as_float(((unsigned)b) << 16); }
; DEVI void h2_item(const Params& P, int l, int pass, int item, int tid) {
;     ...
;   for (int c0 = 0; c0 < 64; c0 += 8) {
;     float u[8], dc[8];
; #pragma unroll
;     for (int i = 0; i < 8; ++i) { u[i] = b2f(US[(long)(c0 + i) << 14]); dc[i] = dec[(c0 + i) * 128]; }
; #pragma unroll
;     for (int i = 0; i < 8; ++i) { US[(long)(c0 + i) << 14] = f2b(S); S = dc[i] * S + u[i]; }
;   }
	v_lshlrev_b32_e32 v196, 16, v196
	s_waitcnt vmcnt(39)
	v_fmac_f32_e32 v196, v4, v197
	v_bfe_u32 v212, v196, 16, 1
	v_add3_u32 v212, v196, v212, s39
	global_store_short_d16_hi v[216:217], v212, off
	s_waitcnt vmcnt(33)
	v_lshlrev_b32_e32 v4, 16, v204
	s_waitcnt vmcnt(32)
	v_lshlrev_b32_e32 v213, 16, v205
	v_fmac_f32_e32 v4, v198, v196
	v_bfe_u32 v212, v4, 16, 1
	v_fmac_f32_e32 v213, v199, v4
	s_waitcnt vmcnt(31)
	v_lshlrev_b32_e32 v196, 16, v206
	s_waitcnt vmcnt(30)
	v_lshlrev_b32_e32 v215, 16, v207
	v_add3_u32 v4, v4, v212, s39
	v_bfe_u32 v212, v213, 16, 1
	v_fmac_f32_e32 v196, v200, v213
	global_store_short_d16_hi v[218:219], v4, off
	s_waitcnt vmcnt(30)
	v_lshlrev_b32_e32 v216, 16, v208
	v_add3_u32 v4, v213, v212, s39
	v_bfe_u32 v212, v196, 16, 1
	v_fmac_f32_e32 v215, v201, v196
	global_store_short_d16_hi v[220:221], v4, off
	s_waitcnt vmcnt(30)
	v_lshlrev_b32_e32 v213, 16, v209
	v_add3_u32 v4, v196, v212, s39
	v_bfe_u32 v196, v215, 16, 1
	v_fmac_f32_e32 v216, v202, v215
	s_waitcnt vmcnt(29)
	v_lshlrev_b32_e32 v212, 16, v210
	global_store_short_d16_hi v[222:223], v4, off
	v_add3_u32 v4, v215, v196, s39
	v_bfe_u32 v196, v216, 16, 1
	v_fmac_f32_e32 v213, v203, v216
	global_store_short_d16_hi v[224:225], v4, off
	v_add3_u32 v196, v216, v196, s39
	v_bfe_u32 v215, v213, 16, 1
	v_mov_b32_e32 v4, v212
	global_store_short_d16_hi v[226:227], v196, off
	v_add3_u32 v196, v213, v215, s39
	s_waitcnt vmcnt(31)
	v_fmac_f32_e32 v4, v214, v213
	global_store_short_d16_hi v[228:229], v196, off
	v_lshl_add_u64 v[212:213], v[64:65], 0, v[0:1]
	v_add_co_u32_e32 v216, vcc, 0x8000, v212
	s_mov_b32 s46, 0x10000
	s_nop 0
	v_addc_co_u32_e32 v217, vcc, 0, v213, vcc
	v_add_co_u32_e32 v218, vcc, s46, v212
	v_lshl_add_u64 v[214:215], v[64:65], 0, v[2:3]
	s_nop 0
	v_addc_co_u32_e32 v219, vcc, 0, v213, vcc
	v_add_co_u32_e32 v220, vcc, 0x18000, v212
	global_load_ushort v196, v[212:213], off
	global_load_dword v197, v[214:215], off
	global_load_dword v198, v[214:215], off offset:512
	global_load_dword v199, v[214:215], off offset:1024
	global_load_dword v200, v[214:215], off offset:1536
	global_load_dword v201, v[214:215], off offset:2048
	global_load_dword v202, v[214:215], off offset:2560
	global_load_dword v203, v[214:215], off offset:3072
	v_addc_co_u32_e32 v221, vcc, 0, v213, vcc
	v_add_co_u32_e32 v222, vcc, s6, v212
	global_load_ushort v204, v[216:217], off
	global_load_ushort v205, v[218:219], off
	v_addc_co_u32_e32 v223, vcc, 0, v213, vcc
	v_add_co_u32_e32 v224, vcc, 0x28000, v212
	global_load_ushort v206, v[220:221], off
	global_load_ushort v207, v[222:223], off
	v_addc_co_u32_e32 v225, vcc, 0, v213, vcc
	v_add_co_u32_e32 v226, vcc, 0x30000, v212
	global_load_ushort v208, v[224:225], off
	s_nop 0
	v_addc_co_u32_e32 v227, vcc, 0, v213, vcc
	v_add_co_u32_e32 v228, vcc, 0x38000, v212
	global_load_ushort v209, v[226:227], off
	s_nop 0
	v_addc_co_u32_e32 v229, vcc, 0, v213, vcc
	global_load_ushort v210, v[228:229], off
	s_nop 0
	global_load_dword v214, v[214:215], off offset:3584
	v_lshl_add_u64 v[0:1], v[0:1], 0, s[8:9]
	v_lshl_add_u64 v[2:3], v[2:3], 0, s[4:5]
	v_bfe_u32 v9, v4, 16, 1
	v_add3_u32 v9, v4, v9, s39
	global_store_short_d16_hi v[6:7], v9, off
	s_waitcnt vmcnt(40)
	v_lshlrev_b32_e32 v5, 16, v5
	s_waitcnt vmcnt(39)
	v_fmac_f32_e32 v5, v4, v41
	v_bfe_u32 v6, v5, 16, 1
	v_add3_u32 v6, v5, v6, s39
	global_store_short_d16_hi v[10:11], v6, off
	s_waitcnt vmcnt(33)
	v_lshlrev_b32_e32 v4, 16, v55
	s_waitcnt vmcnt(32)
	v_lshlrev_b32_e32 v7, 16, v56
	v_fmac_f32_e32 v4, v43, v5
	v_bfe_u32 v6, v4, 16, 1
	v_fmac_f32_e32 v7, v45, v4
	s_waitcnt vmcnt(31)
	v_lshlrev_b32_e32 v5, 16, v57
	s_waitcnt vmcnt(30)
	v_lshlrev_b32_e32 v9, 16, v58
	v_add3_u32 v4, v4, v6, s39
	v_bfe_u32 v6, v7, 16, 1
	v_fmac_f32_e32 v5, v47, v7
	global_store_short_d16_hi v[12:13], v4, off
	s_waitcnt vmcnt(30)
	v_lshlrev_b32_e32 v10, 16, v59
	v_add3_u32 v4, v7, v6, s39
	v_bfe_u32 v6, v5, 16, 1
	v_fmac_f32_e32 v9, v52, v5
	global_store_short_d16_hi v[14:15], v4, off
	s_waitcnt vmcnt(30)
	v_lshlrev_b32_e32 v7, 16, v60
	v_add3_u32 v4, v5, v6, s39
	v_bfe_u32 v5, v9, 16, 1
	v_fmac_f32_e32 v10, v53, v9
	s_waitcnt vmcnt(29)
	v_lshlrev_b32_e32 v6, 16, v61
	global_store_short_d16_hi v[16:17], v4, off
	v_add3_u32 v4, v9, v5, s39
	v_bfe_u32 v5, v10, 16, 1
	v_fmac_f32_e32 v7, v54, v10
	global_store_short_d16_hi v[18:19], v4, off
	v_add3_u32 v5, v10, v5, s39
	v_bfe_u32 v9, v7, 16, 1
	v_mov_b32_e32 v4, v6
	global_store_short_d16_hi v[48:49], v5, off
	v_add3_u32 v5, v7, v9, s39
	s_waitcnt vmcnt(31)
	v_fmac_f32_e32 v4, v8, v7
	global_store_short_d16_hi v[50:51], v5, off
	v_lshl_add_u64 v[6:7], v[64:65], 0, v[0:1]
	v_add_co_u32_e32 v10, vcc, 0x8000, v6
	s_mov_b32 s46, 0x10000
	s_nop 0
	v_addc_co_u32_e32 v11, vcc, 0, v7, vcc
	v_add_co_u32_e32 v12, vcc, s46, v6
	v_lshl_add_u64 v[8:9], v[64:65], 0, v[2:3]
	s_nop 0
	v_addc_co_u32_e32 v13, vcc, 0, v7, vcc
	v_add_co_u32_e32 v14, vcc, 0x18000, v6
	global_load_ushort v5, v[6:7], off
	global_load_dword v41, v[8:9], off
	global_load_dword v43, v[8:9], off offset:512
	global_load_dword v45, v[8:9], off offset:1024
	global_load_dword v47, v[8:9], off offset:1536
	global_load_dword v52, v[8:9], off offset:2048
	global_load_dword v53, v[8:9], off offset:2560
	global_load_dword v54, v[8:9], off offset:3072
	v_addc_co_u32_e32 v15, vcc, 0, v7, vcc
	v_add_co_u32_e32 v16, vcc, s6, v6
	global_load_ushort v55, v[10:11], off
	global_load_ushort v56, v[12:13], off
	v_addc_co_u32_e32 v17, vcc, 0, v7, vcc
	v_add_co_u32_e32 v18, vcc, 0x28000, v6
	global_load_ushort v57, v[14:15], off
	global_load_ushort v58, v[16:17], off
	v_addc_co_u32_e32 v19, vcc, 0, v7, vcc
	v_add_co_u32_e32 v48, vcc, 0x30000, v6
	global_load_ushort v59, v[18:19], off
	s_nop 0
	v_addc_co_u32_e32 v49, vcc, 0, v7, vcc
	v_add_co_u32_e32 v50, vcc, 0x38000, v6
	global_load_ushort v60, v[48:49], off
	s_nop 0
	v_addc_co_u32_e32 v51, vcc, 0, v7, vcc
	global_load_ushort v61, v[50:51], off
	s_nop 0
	global_load_dword v8, v[8:9], off offset:3584
	v_lshl_add_u64 v[0:1], v[0:1], 0, s[8:9]
	v_lshl_add_u64 v[2:3], v[2:3], 0, s[4:5]
	v_bfe_u32 v215, v4, 16, 1
	v_add3_u32 v215, v4, v215, s39
	global_store_short_d16_hi v[212:213], v215, off
	s_waitcnt vmcnt(40)
; DEVI float b2f(bfu b) { return __uint_as_float(((unsigned)b) << 16); }
; DEVI void h2_item(const Params& P, int l, int pass, int item, int tid) {
;     ...
;   for (int c0 = 0; c0 < 64; c0 += 8) {
;     float u[8], dc[8];
; #pragma unroll
;     for (int i = 0; i < 8; ++i) { u[i] = b2f(US[(long)(c0 + i) << 14]); dc[i] = dec[(c0 + i) * 128]; }
; #pragma unroll
;     for (int i = 0; i < 8; ++i) { US[(long)(c0 + i) << 14] = f2b(S); S = dc[i] * S + u[i]; }
;   }
	v_lshlrev_b32_e32 v196, 16, v196
	s_waitcnt vmcnt(39)
	v_fmac_f32_e32 v196, v4, v197
	v_bfe_u32 v212, v196, 16, 1
	v_add3_u32 v212, v196, v212, s39
	global_store_short_d16_hi v[216:217], v212, off
	s_waitcnt vmcnt(33)
	v_lshlrev_b32_e32 v4, 16, v204
	s_waitcnt vmcnt(32)
	v_lshlrev_b32_e32 v213, 16, v205
	v_fmac_f32_e32 v4, v198, v196
	v_bfe_u32 v212, v4, 16, 1
	v_fmac_f32_e32 v213, v199, v4
	s_waitcnt vmcnt(31)
	v_lshlrev_b32_e32 v196, 16, v206
	s_waitcnt vmcnt(30)
	v_lshlrev_b32_e32 v215, 16, v207
	v_add3_u32 v4, v4, v212, s39
	v_bfe_u32 v212, v213, 16, 1
	v_fmac_f32_e32 v196, v200, v213
	global_store_short_d16_hi v[218:219], v4, off
	s_waitcnt vmcnt(30)
	v_lshlrev_b32_e32 v216, 16, v208
	v_add3_u32 v4, v213, v212, s39
	v_bfe_u32 v212, v196, 16, 1
	v_fmac_f32_e32 v215, v201, v196
	global_store_short_d16_hi v[220:221], v4, off
	s_waitcnt vmcnt(30)
	v_lshlrev_b32_e32 v213, 16, v209
	v_add3_u32 v4, v196, v212, s39
	v_bfe_u32 v196, v215, 16, 1
	v_fmac_f32_e32 v216, v202, v215
	s_waitcnt vmcnt(29)
	v_lshlrev_b32_e32 v212, 16, v210
	global_store_short_d16_hi v[222:223], v4, off
	v_add3_u32 v4, v215, v196, s39
	v_bfe_u32 v196, v216, 16, 1
	v_fmac_f32_e32 v213, v203, v216
	global_store_short_d16_hi v[224:225], v4, off
	v_add3_u32 v196, v216, v196, s39
	v_bfe_u32 v215, v213, 16, 1
	v_mov_b32_e32 v4, v212
	global_store_short_d16_hi v[226:227], v196, off
	v_add3_u32 v196, v213, v215, s39
	s_waitcnt vmcnt(31)
	v_fmac_f32_e32 v4, v214, v213
	global_store_short_d16_hi v[228:229], v196, off
	v_lshl_add_u64 v[212:213], v[64:65], 0, v[0:1]
	v_add_co_u32_e32 v216, vcc, 0x8000, v212
	s_mov_b32 s46, 0x10000
	s_nop 0
	v_addc_co_u32_e32 v217, vcc, 0, v213, vcc
	v_add_co_u32_e32 v218, vcc, s46, v212
	v_lshl_add_u64 v[214:215], v[64:65], 0, v[2:3]
	s_nop 0
	v_addc_co_u32_e32 v219, vcc, 0, v213, vcc
	v_add_co_u32_e32 v220, vcc, 0x18000, v212
	global_load_ushort v196, v[212:213], off
	global_load_dword v197, v[214:215], off
	global_load_dword v198, v[214:215], off offset:512
	global_load_dword v199, v[214:215], off offset:1024
	global_load_dword v200, v[214:215], off offset:1536
	global_load_dword v201, v[214:215], off offset:2048
	global_load_dword v202, v[214:215], off offset:2560
	global_load_dword v203, v[214:215], off offset:3072
	v_addc_co_u32_e32 v221, vcc, 0, v213, vcc
	v_add_co_u32_e32 v222, vcc, s6, v212
	global_load_ushort v204, v[216:217], off
	global_load_ushort v205, v[218:219], off
	v_addc_co_u32_e32 v223, vcc, 0, v213, vcc
	v_add_co_u32_e32 v224, vcc, 0x28000, v212
	global_load_ushort v206, v[220:221], off
	global_load_ushort v207, v[222:223], off
	v_addc_co_u32_e32 v225, vcc, 0, v213, vcc
	v_add_co_u32_e32 v226, vcc, 0x30000, v212
	global_load_ushort v208, v[224:225], off
	s_nop 0
	v_addc_co_u32_e32 v227, vcc, 0, v213, vcc
	v_add_co_u32_e32 v228, vcc, 0x38000, v212
	global_load_ushort v209, v[226:227], off
	s_nop 0
	v_addc_co_u32_e32 v229, vcc, 0, v213, vcc
	global_load_ushort v210, v[228:229], off
	s_nop 0
	global_load_dword v214, v[214:215], off offset:3584
	v_lshl_add_u64 v[0:1], v[0:1], 0, s[8:9]
	v_lshl_add_u64 v[2:3], v[2:3], 0, s[4:5]
	v_bfe_u32 v9, v4, 16, 1
	v_add3_u32 v9, v4, v9, s39
	global_store_short_d16_hi v[6:7], v9, off
	s_waitcnt vmcnt(40)
	v_lshlrev_b32_e32 v5, 16, v5
	s_waitcnt vmcnt(39)
	v_fmac_f32_e32 v5, v4, v41
	v_bfe_u32 v6, v5, 16, 1
	v_add3_u32 v6, v5, v6, s39
	global_store_short_d16_hi v[10:11], v6, off
	s_waitcnt vmcnt(33)
	v_lshlrev_b32_e32 v4, 16, v55
	s_waitcnt vmcnt(32)
	v_lshlrev_b32_e32 v7, 16, v56
	v_fmac_f32_e32 v4, v43, v5
	v_bfe_u32 v6, v4, 16, 1
	v_fmac_f32_e32 v7, v45, v4
	s_waitcnt vmcnt(31)
	v_lshlrev_b32_e32 v5, 16, v57
	s_waitcnt vmcnt(30)
	v_lshlrev_b32_e32 v9, 16, v58
	v_add3_u32 v4, v4, v6, s39
	v_bfe_u32 v6, v7, 16, 1
	v_fmac_f32_e32 v5, v47, v7
	global_store_short_d16_hi v[12:13], v4, off
	s_waitcnt vmcnt(30)
	v_lshlrev_b32_e32 v10, 16, v59
	v_add3_u32 v4, v7, v6, s39
	v_bfe_u32 v6, v5, 16, 1
	v_fmac_f32_e32 v9, v52, v5
	global_store_short_d16_hi v[14:15], v4, off
	s_waitcnt vmcnt(30)
	v_lshlrev_b32_e32 v7, 16, v60
	v_add3_u32 v4, v5, v6, s39
	v_bfe_u32 v5, v9, 16, 1
	v_fmac_f32_e32 v10, v53, v9
	s_waitcnt vmcnt(29)
	v_lshlrev_b32_e32 v6, 16, v61
	global_store_short_d16_hi v[16:17], v4, off
	v_add3_u32 v4, v9, v5, s39
	v_bfe_u32 v5, v10, 16, 1
	v_fmac_f32_e32 v7, v54, v10
	global_store_short_d16_hi v[18:19], v4, off
	v_add3_u32 v5, v10, v5, s39
	v_bfe_u32 v9, v7, 16, 1
	v_mov_b32_e32 v4, v6
	global_store_short_d16_hi v[48:49], v5, off
	v_add3_u32 v5, v7, v9, s39
	s_waitcnt vmcnt(31)
	v_fmac_f32_e32 v4, v8, v7
	global_store_short_d16_hi v[50:51], v5, off
	v_lshl_add_u64 v[6:7], v[64:65], 0, v[0:1]
	v_add_co_u32_e32 v10, vcc, 0x8000, v6
	s_mov_b32 s46, 0x10000
	s_nop 0
	v_addc_co_u32_e32 v11, vcc, 0, v7, vcc
	v_add_co_u32_e32 v12, vcc, s46, v6
	v_lshl_add_u64 v[8:9], v[64:65], 0, v[2:3]
	s_nop 0
	v_addc_co_u32_e32 v13, vcc, 0, v7, vcc
	v_add_co_u32_e32 v14, vcc, 0x18000, v6
	global_load_ushort v5, v[6:7], off
	global_load_dword v41, v[8:9], off
	global_load_dword v43, v[8:9], off offset:512
	global_load_dword v45, v[8:9], off offset:1024
	global_load_dword v47, v[8:9], off offset:1536
	global_load_dword v52, v[8:9], off offset:2048
	global_load_dword v53, v[8:9], off offset:2560
	global_load_dword v54, v[8:9], off offset:3072
	v_addc_co_u32_e32 v15, vcc, 0, v7, vcc
	v_add_co_u32_e32 v16, vcc, s6, v6
	global_load_ushort v55, v[10:11], off
	global_load_ushort v56, v[12:13], off
	v_addc_co_u32_e32 v17, vcc, 0, v7, vcc
	v_add_co_u32_e32 v18, vcc, 0x28000, v6
	global_load_ushort v57, v[14:15], off
	global_load_ushort v58, v[16:17], off
	v_addc_co_u32_e32 v19, vcc, 0, v7, vcc
	v_add_co_u32_e32 v48, vcc, 0x30000, v6
	global_load_ushort v59, v[18:19], off
	s_nop 0
	v_addc_co_u32_e32 v49, vcc, 0, v7, vcc
	v_add_co_u32_e32 v50, vcc, 0x38000, v6
	global_load_ushort v60, v[48:49], off
	s_nop 0
	v_addc_co_u32_e32 v51, vcc, 0, v7, vcc
	global_load_ushort v61, v[50:51], off
	s_nop 0
	global_load_dword v8, v[8:9], off offset:3584
	v_lshl_add_u64 v[0:1], v[0:1], 0, s[8:9]
	v_lshl_add_u64 v[2:3], v[2:3], 0, s[4:5]
	v_bfe_u32 v215, v4, 16, 1
	v_add3_u32 v215, v4, v215, s39
	global_store_short_d16_hi v[212:213], v215, off
	s_waitcnt vmcnt(40)
; DEVI float b2f(bfu b) { return __uint_as_float(((unsigned)b) << 16); }
; DEVI void h2_item(const Params& P, int l, int pass, int item, int tid) {
;     ...
;   for (int c0 = 0; c0 < 64; c0 += 8) {
;     float u[8], dc[8];
; #pragma unroll
;     for (int i = 0; i < 8; ++i) { u[i] = b2f(US[(long)(c0 + i) << 14]); dc[i] = dec[(c0 + i) * 128]; }
; #pragma unroll
;     for (int i = 0; i < 8; ++i) { US[(long)(c0 + i) << 14] = f2b(S); S = dc[i] * S + u[i]; }
;   }
;   const int sl = sh >> 3, h = sh & 7, b = pass * 2 + sl;
;   P.out[OUT_HGP + (((long)((l * 4 + b) * 8 + h)) << 14) + d * 128 + e] = S;
	v_lshlrev_b32_e32 v196, 16, v196
	s_waitcnt vmcnt(39)
	v_fmac_f32_e32 v196, v4, v197
	v_bfe_u32 v212, v196, 16, 1
	v_add3_u32 v212, v196, v212, s39
	global_store_short_d16_hi v[216:217], v212, off
	s_waitcnt vmcnt(33)
	v_lshlrev_b32_e32 v4, 16, v204
	s_waitcnt vmcnt(32)
	v_lshlrev_b32_e32 v213, 16, v205
	v_fmac_f32_e32 v4, v198, v196
	v_bfe_u32 v212, v4, 16, 1
	v_fmac_f32_e32 v213, v199, v4
	s_waitcnt vmcnt(31)
	v_lshlrev_b32_e32 v196, 16, v206
	s_waitcnt vmcnt(30)
	v_lshlrev_b32_e32 v215, 16, v207
	v_add3_u32 v4, v4, v212, s39
	v_bfe_u32 v212, v213, 16, 1
	v_fmac_f32_e32 v196, v200, v213
	global_store_short_d16_hi v[218:219], v4, off
	s_waitcnt vmcnt(30)
	v_lshlrev_b32_e32 v216, 16, v208
	v_add3_u32 v4, v213, v212, s39
	v_bfe_u32 v212, v196, 16, 1
	v_fmac_f32_e32 v215, v201, v196
	global_store_short_d16_hi v[220:221], v4, off
	s_waitcnt vmcnt(30)
	v_lshlrev_b32_e32 v213, 16, v209
	v_add3_u32 v4, v196, v212, s39
	v_bfe_u32 v196, v215, 16, 1
	v_fmac_f32_e32 v216, v202, v215
	s_waitcnt vmcnt(29)
	v_lshlrev_b32_e32 v212, 16, v210
	global_store_short_d16_hi v[222:223], v4, off
	v_add3_u32 v4, v215, v196, s39
	v_bfe_u32 v196, v216, 16, 1
	v_fmac_f32_e32 v213, v203, v216
	global_store_short_d16_hi v[224:225], v4, off
	v_add3_u32 v196, v216, v196, s39
	v_bfe_u32 v215, v213, 16, 1
	v_mov_b32_e32 v4, v212
	global_store_short_d16_hi v[226:227], v196, off
	v_add3_u32 v196, v213, v215, s39
	s_waitcnt vmcnt(31)
	v_fmac_f32_e32 v4, v214, v213
	global_store_short_d16_hi v[228:229], v196, off
	v_lshl_add_u64 v[212:213], v[64:65], 0, v[0:1]
	v_add_co_u32_e32 v216, vcc, 0x8000, v212
	s_mov_b32 s46, 0x10000
	s_nop 0
	v_addc_co_u32_e32 v217, vcc, 0, v213, vcc
	v_add_co_u32_e32 v218, vcc, s46, v212
	v_lshl_add_u64 v[214:215], v[64:65], 0, v[2:3]
	s_nop 0
	v_addc_co_u32_e32 v219, vcc, 0, v213, vcc
	v_add_co_u32_e32 v220, vcc, 0x18000, v212
	global_load_ushort v196, v[212:213], off
	global_load_dword v197, v[214:215], off
	global_load_dword v198, v[214:215], off offset:512
	global_load_dword v199, v[214:215], off offset:1024
	global_load_dword v200, v[214:215], off offset:1536
	global_load_dword v201, v[214:215], off offset:2048
	global_load_dword v202, v[214:215], off offset:2560
	global_load_dword v203, v[214:215], off offset:3072
	v_addc_co_u32_e32 v221, vcc, 0, v213, vcc
	v_add_co_u32_e32 v222, vcc, s6, v212
	global_load_ushort v204, v[216:217], off
	global_load_ushort v205, v[218:219], off
	v_addc_co_u32_e32 v223, vcc, 0, v213, vcc
	v_add_co_u32_e32 v224, vcc, 0x28000, v212
	global_load_ushort v206, v[220:221], off
	global_load_ushort v207, v[222:223], off
	v_addc_co_u32_e32 v225, vcc, 0, v213, vcc
	v_add_co_u32_e32 v226, vcc, 0x30000, v212
	global_load_ushort v208, v[224:225], off
	s_nop 0
	v_addc_co_u32_e32 v227, vcc, 0, v213, vcc
	v_add_co_u32_e32 v228, vcc, 0x38000, v212
	global_load_ushort v209, v[226:227], off
	s_nop 0
	v_addc_co_u32_e32 v229, vcc, 0, v213, vcc
	global_load_ushort v210, v[228:229], off
	s_nop 0
	global_load_dword v214, v[214:215], off offset:3584
	v_lshl_add_u64 v[0:1], v[0:1], 0, s[8:9]
	v_lshl_add_u64 v[2:3], v[2:3], 0, s[4:5]
	v_bfe_u32 v9, v4, 16, 1
	v_add3_u32 v9, v4, v9, s39
	global_store_short_d16_hi v[6:7], v9, off
	s_waitcnt vmcnt(40)
	v_lshlrev_b32_e32 v5, 16, v5
	s_waitcnt vmcnt(39)
	v_fmac_f32_e32 v5, v4, v41
	v_bfe_u32 v6, v5, 16, 1
	v_add3_u32 v6, v5, v6, s39
	global_store_short_d16_hi v[10:11], v6, off
	s_waitcnt vmcnt(33)
	v_lshlrev_b32_e32 v4, 16, v55
	s_waitcnt vmcnt(32)
	v_lshlrev_b32_e32 v7, 16, v56
	v_fmac_f32_e32 v4, v43, v5
	v_bfe_u32 v6, v4, 16, 1
	v_fmac_f32_e32 v7, v45, v4
	s_waitcnt vmcnt(31)
	v_lshlrev_b32_e32 v5, 16, v57
	s_waitcnt vmcnt(30)
	v_lshlrev_b32_e32 v9, 16, v58
	v_add3_u32 v4, v4, v6, s39
	v_bfe_u32 v6, v7, 16, 1
	v_fmac_f32_e32 v5, v47, v7
	global_store_short_d16_hi v[12:13], v4, off
	s_waitcnt vmcnt(30)
	v_lshlrev_b32_e32 v10, 16, v59
	v_add3_u32 v4, v7, v6, s39
	v_bfe_u32 v6, v5, 16, 1
	v_fmac_f32_e32 v9, v52, v5
	global_store_short_d16_hi v[14:15], v4, off
	s_waitcnt vmcnt(30)
	v_lshlrev_b32_e32 v7, 16, v60
	v_add3_u32 v4, v5, v6, s39
	v_bfe_u32 v5, v9, 16, 1
	v_fmac_f32_e32 v10, v53, v9
	s_waitcnt vmcnt(29)
	v_lshlrev_b32_e32 v6, 16, v61
	global_store_short_d16_hi v[16:17], v4, off
	v_add3_u32 v4, v9, v5, s39
	v_bfe_u32 v5, v10, 16, 1
	v_fmac_f32_e32 v7, v54, v10
	global_store_short_d16_hi v[18:19], v4, off
	v_add3_u32 v5, v10, v5, s39
	v_bfe_u32 v9, v7, 16, 1
	v_mov_b32_e32 v4, v6
	global_store_short_d16_hi v[48:49], v5, off
	v_add3_u32 v5, v7, v9, s39
	s_waitcnt vmcnt(31)
	v_fmac_f32_e32 v4, v8, v7
	global_store_short_d16_hi v[50:51], v5, off
	v_bfe_u32 v215, v4, 16, 1
	v_add3_u32 v215, v4, v215, s39
	global_store_short_d16_hi v[212:213], v215, off
	s_waitcnt vmcnt(24)
	v_lshlrev_b32_e32 v196, 16, v196
	s_waitcnt vmcnt(23)
	v_fmac_f32_e32 v196, v4, v197
	v_bfe_u32 v212, v196, 16, 1
	v_add3_u32 v212, v196, v212, s39
	global_store_short_d16_hi v[216:217], v212, off
	s_waitcnt vmcnt(17)
	v_lshlrev_b32_e32 v4, 16, v204
	s_waitcnt vmcnt(16)
	v_lshlrev_b32_e32 v213, 16, v205
	v_fmac_f32_e32 v4, v198, v196
	v_bfe_u32 v212, v4, 16, 1
	v_fmac_f32_e32 v213, v199, v4
	s_waitcnt vmcnt(15)
	v_lshlrev_b32_e32 v196, 16, v206
	s_waitcnt vmcnt(14)
	v_lshlrev_b32_e32 v215, 16, v207
	v_add3_u32 v4, v4, v212, s39
	v_bfe_u32 v212, v213, 16, 1
	v_fmac_f32_e32 v196, v200, v213
	global_store_short_d16_hi v[218:219], v4, off
	s_waitcnt vmcnt(14)
	v_lshlrev_b32_e32 v216, 16, v208
	v_add3_u32 v4, v213, v212, s39
	v_bfe_u32 v212, v196, 16, 1
	v_fmac_f32_e32 v215, v201, v196
	global_store_short_d16_hi v[220:221], v4, off
	s_waitcnt vmcnt(14)
	v_lshlrev_b32_e32 v213, 16, v209
	v_add3_u32 v4, v196, v212, s39
	v_bfe_u32 v196, v215, 16, 1
	v_fmac_f32_e32 v216, v202, v215
	s_waitcnt vmcnt(13)
	v_lshlrev_b32_e32 v212, 16, v210
	global_store_short_d16_hi v[222:223], v4, off
	v_add3_u32 v4, v215, v196, s39
	v_bfe_u32 v196, v216, 16, 1
	v_fmac_f32_e32 v213, v203, v216
	global_store_short_d16_hi v[224:225], v4, off
	v_add3_u32 v196, v216, v196, s39
	v_bfe_u32 v215, v213, 16, 1
	v_mov_b32_e32 v4, v212
	global_store_short_d16_hi v[226:227], v196, off
	v_add3_u32 v196, v213, v215, s39
	s_waitcnt vmcnt(15)
	v_fmac_f32_e32 v4, v214, v213
	global_store_short_d16_hi v[228:229], v196, off
	s_sub_i32 s24, s59, s1
	s_lshr_b32 s46, s24, 6
	s_and_b32 s46, s46, 0x3fffff8
	s_lshl_b32 s47, s24, 8
	s_bfe_u32 s24, s24, 0x30006
	s_add_i32 s46, s56, s46
	s_and_b32 s47, s47, 0x3f00
	s_or_b32 s46, s46, s24
	v_add_u32_e32 v0, s47, v20
	s_ashr_i32 s47, s46, 31
	s_lshl_b64 s[46:47], s[46:47], 16
	s_add_u32 s46, s28, s46
	v_ashrrev_i32_e32 v0, 7, v0
	s_addc_u32 s47, s29, s47
	v_mov_b32_e32 v41, v89
	v_ashrrev_i32_e32 v1, 31, v0
	v_lshl_add_u64 v[2:3], s[46:47], 0, v[40:41]
	v_lshl_add_u64 v[0:1], v[0:1], 2, v[2:3]
	v_add_co_u32_e32 v0, vcc, 0x4130000, v0
	s_mov_b64 s[76:77], 0x40000
	s_nop 0
	v_addc_co_u32_e32 v1, vcc, 0, v1, vcc
	s_mov_b64 s[46:47], 0
	global_store_dword v[0:1], v4, off
